# strategy 6 (LDS bank conflicts): the VT staging image of p3a S1 is written through an XOR swizzle of the 16-byte chunk index (8-way conflict on every ds_write_b128 removed); the S3 copy reads it back
# speedup vs baseline: 1.0071x; 1.0062x over previous
.LBB0_532:
	s_or_b64 exec, exec, s[8:9]
	v_cmp_lt_i32_e32 vcc, 31, v160
	s_and_saveexec_b64 s[8:9], vcc
	s_cbranch_execz .LBB0_534
	v_cvt_pk_bf16_f32 v162, v20, v28
	v_lshl_add_u32 v19, v160, 10, v188
	v_lshlrev_b32_e32 v20, 7, v160
	v_and_b32_e32 v19, 0x7fffc000, v19
	v_and_b32_e32 v20, 0x780, v20
	v_readlane_b32 s10, v249, 54
	v_cvt_pk_bf16_f32 v68, v68, v84
	v_cvt_pk_bf16_f32 v84, v69, v85
	v_cvt_pk_bf16_f32 v58, v58, v66
	v_cvt_pk_bf16_f32 v96, v59, v67
	v_cvt_pk_bf16_f32 v67, v42, v50
	v_cvt_pk_bf16_f32 v66, v26, v34
	v_cvt_pk_bf16_f32 v69, v52, v60
	v_add3_u32 v19, s10, v19, v20
	v_and_b32_e32 v226, 7, v160
	v_lshl_or_b32 v19, v226, 4, v19
	v_cvt_pk_bf16_f32 v88, v62, v72
	v_cvt_pk_bf16_f32 v92, v63, v73
	v_cvt_pk_bf16_f32 v164, v56, v54
	v_cvt_pk_bf16_f32 v170, v57, v55
	v_cvt_pk_bf16_f32 v83, v43, v51
	v_cvt_pk_bf16_f32 v87, v40, v48
	v_cvt_pk_bf16_f32 v91, v41, v49
	v_cvt_pk_bf16_f32 v57, v38, v46
	v_cvt_pk_bf16_f32 v95, v39, v47
	v_cvt_pk_bf16_f32 v163, v36, v44
	v_cvt_pk_bf16_f32 v169, v37, v45
	v_cvt_pk_bf16_f32 v82, v27, v35
	v_cvt_pk_bf16_f32 v86, v24, v32
	v_cvt_pk_bf16_f32 v90, v25, v33
	v_cvt_pk_bf16_f32 v56, v22, v30
	v_cvt_pk_bf16_f32 v94, v23, v31
	v_cvt_pk_bf16_f32 v168, v21, v29
	v_cvt_pk_bf16_f32 v171, v79, v81
	v_cvt_pk_bf16_f32 v165, v78, v80
	v_cvt_pk_bf16_f32 v97, v71, v77
	v_cvt_pk_bf16_f32 v59, v70, v76
	v_cvt_pk_bf16_f32 v93, v65, v75
	v_cvt_pk_bf16_f32 v89, v64, v74
	v_cvt_pk_bf16_f32 v85, v53, v61
	v_xor_b32_e32 v226, 16, v19
	v_xor_b32_e32 v227, 32, v19
	v_xor_b32_e32 v228, 48, v19
	v_xor_b32_e32 v229, 64, v19
	v_xor_b32_e32 v230, 0x50, v19
	v_xor_b32_e32 v231, 0x60, v19
	v_xor_b32_e32 v232, 0x70, v19
	ds_write_b128 v19, v[66:69] offset:32768
	ds_write_b128 v226, v[82:85] offset:32768
	ds_write_b128 v227, v[86:89] offset:32768
	ds_write_b128 v228, v[90:93] offset:32768
	ds_write_b128 v229, v[56:59] offset:32768
	ds_write_b128 v230, v[94:97] offset:32768
	ds_write_b128 v231, v[162:165] offset:32768
	ds_write_b128 v232, v[168:171] offset:32768

.LBB0_641:
	s_and_b64 vcc, exec, s[4:5]
	s_cbranch_vccz .LBB0_651
	v_readlane_b32 s4, v248, 0
	v_readlane_b32 s5, v248, 1
	s_andn2_b64 vcc, exec, s[4:5]
	s_mov_b64 s[4:5], -1
	s_cbranch_vccnz .LBB0_648
	s_lshl_b32 s6, s42, 1
	s_add_i32 s4, s6, s72
	s_lshr_b32 s5, s4, 4
	s_cmp_eq_u32 s5, 2
	s_cselect_b32 s7, s17, 0x26000000
	s_cmp_lg_u32 s5, 1
	s_cselect_b32 s5, s7, 0x1d000000
	s_cmp_gt_u32 s4, 15
	s_cselect_b32 s4, s5, 0x1ed00000
	s_add_u32 s4, s70, s4
	s_addc_u32 s5, s71, 0
	s_lshl_b32 s8, s42, 7
	s_and_b32 s8, s8, 0x380
	s_add_i32 s8, s8, s85
	s_mul_hi_i32 s9, s8, 0x7400
	s_mulk_i32 s8, 0x7400
	s_add_u32 s4, s4, s8
	s_addc_u32 s5, s5, s9
	s_add_u32 s4, s4, 0x3000
	s_addc_u32 s5, s5, 0
	s_add_i32 s8, 0, 0x8000
	s_mov_b32 s7, 0
	v_bfe_u32 v10, v160, 3, 3
	v_xor_b32_e32 v10, v10, v160
	v_lshl_add_u32 v2, v10, 4, s8
.LBB0_644:
	v_add_u32_e32 v8, s7, v19
	v_add_u32_e32 v3, s7, v2
	ds_read_b128 v[4:7], v3
	ds_read_b128 v[12:15], v3 offset:1024
	ds_read_b128 v[228:231], v3 offset:2048
	ds_read_b128 v[232:235], v3 offset:3072
	ds_read_b128 v[236:239], v3 offset:4096
	ds_read_b128 v[240:243], v3 offset:5120
	ds_read_b128 v[244:247], v3 offset:6144
	ds_read_b128 v[98:101], v3 offset:7168
	v_add_u32_e32 v9, 0x1000, v8
	s_waitcnt lgkmcnt(7)
	global_store_dwordx4 v8, v[4:7], s[4:5] sc0 sc1
	s_waitcnt lgkmcnt(6)
	global_store_dwordx4 v8, v[12:15], s[4:5] offset:1024 sc0 sc1
	s_waitcnt lgkmcnt(5)
	global_store_dwordx4 v8, v[228:231], s[4:5] offset:2048 sc0 sc1
	s_waitcnt lgkmcnt(4)
	global_store_dwordx4 v8, v[232:235], s[4:5] offset:3072 sc0 sc1
	s_waitcnt lgkmcnt(3)
	global_store_dwordx4 v9, v[236:239], s[4:5] sc0 sc1
	s_waitcnt lgkmcnt(2)
	global_store_dwordx4 v9, v[240:243], s[4:5] offset:1024 sc0 sc1
	s_waitcnt lgkmcnt(1)
	global_store_dwordx4 v9, v[244:247], s[4:5] offset:2048 sc0 sc1
	s_waitcnt lgkmcnt(0)
	global_store_dwordx4 v9, v[98:101], s[4:5] offset:3072 sc0 sc1
	s_addk_i32 s7, 0x2000
	s_cmpk_eq_i32 s7, 0x4000
	s_cbranch_scc0 .LBB0_644
	s_or_b32 s4, s6, 1
	s_add_i32 s5, s4, s72
	s_lshr_b32 s6, s5, 4
	s_cmp_eq_u32 s6, 2
	s_cselect_b32 s7, s17, 0x26000000
	s_cmp_lg_u32 s6, 1
	s_cselect_b32 s6, s7, 0x1d000000
	s_cmp_gt_u32 s5, 15
	s_cselect_b32 s5, s6, 0x1ed00000
	s_add_u32 s5, s70, s5
	s_addc_u32 s7, s71, 0
	s_lshl_b32 s4, s4, 6
	s_and_b32 s4, s4, 0x3c0
	s_add_i32 s4, s4, s85
	s_mul_hi_i32 s8, s4, 0x7400
	s_mulk_i32 s4, 0x7400
	s_add_u32 s4, s5, s4
	s_addc_u32 s5, s7, s8
	s_add_u32 s4, s4, 0x3000
	v_readlane_b32 s7, v248, 16
	s_mov_b32 s6, 0
	s_addc_u32 s5, s5, 0
	v_lshl_add_u32 v2, v10, 4, s7
